# attention: even tile's next-tile global loads issued before the tile barrier (prologue end + loop tail) instead of at the loop head
# baseline (speedup 1.0000x reference)
.LBB0_938:
	v_mov_b32_e32 v199, v218
	s_lshl_b32 s1, s48, 8
	v_readfirstlane_b32 s0, v199
	s_and_b32 s49, s1, 0x300
	s_ashr_i32 s0, s0, 1
	s_xor_b32 s17, s49, 0x700
	s_and_b32 s57, s0, 0xffffffe0
	s_ashr_i32 s10, s48, 5
	v_and_b32_e32 v20, 31, v199
	s_add_i32 s57, s57, s17
	s_ashr_i32 s11, s10, 31
	v_or_b32_e32 v196, s57, v20
	s_lshl_b64 s[30:31], s[10:11], 11
	v_ashrrev_i32_e32 v197, 31, v196
	v_lshl_add_u64 v[194:195], s[30:31], 0, v[196:197]
	v_mov_b64_e32 v[0:1], s[8:9]
	v_mad_u64_u32 v[0:1], s[0:1], v194, s50, v[0:1]
	s_bfe_u32 s16, s48, 0x30002
	s_lshl_b64 s[18:19], s[10:11], 22
	s_lshl_b64 s[0:1], s[10:11], 18
	s_lshl_b32 s10, s10, 3
	s_mul_i32 s52, s16, 0xc0
	s_or_b32 s10, s10, s16
	v_bfe_u32 v21, v199, 5, 1
	v_mad_i32_i24 v1, v195, s50, v1
	s_lshl_b32 s64, s52, 1
	s_ashr_i32 s11, s10, 31
	v_lshl_add_u64 v[0:1], v[0:1], 0, s[64:65]
	v_lshlrev_b32_e32 v180, 4, v21
	s_lshl_b32 s56, s16, 7
	s_lshl_b64 s[20:21], s[10:11], 19
	s_addk_i32 s17, 0x100
	v_lshl_add_u64 v[0:1], v[0:1], 0, v[180:181]
	s_add_u32 s10, s4, s18
	global_load_dwordx4 v[112:115], v[0:1], off
	global_load_dwordx4 v[116:119], v[0:1], off offset:32
	global_load_dwordx4 v[120:123], v[0:1], off offset:64
	global_load_dwordx4 v[124:127], v[0:1], off offset:96
	global_load_dwordx4 v[128:131], v[0:1], off offset:128
	global_load_dwordx4 v[132:135], v[0:1], off offset:160
	global_load_dwordx4 v[136:139], v[0:1], off offset:192
	global_load_dwordx4 v[140:143], v[0:1], off offset:224
	global_load_dwordx4 v[144:147], v[0:1], off offset:256
	global_load_dwordx4 v[148:151], v[0:1], off offset:288
	global_load_dwordx4 v[152:155], v[0:1], off offset:320
	global_load_dwordx4 v[156:159], v[0:1], off offset:352
	s_addc_u32 s11, s33, s19
	s_lshl_b32 s16, s16, 8
	s_add_u32 s22, s10, s16
	v_mov_b32_e32 v0, v199
	s_addc_u32 s23, s11, 0
	s_add_u32 s24, s46, s20
	v_lshrrev_b32_e32 v1, 3, v0
	v_lshlrev_b32_e32 v0, 4, v0
	s_addc_u32 s25, s47, s21
	v_and_b32_e32 v0, 0x70, v0
	s_add_u32 s26, s44, s0
	v_lshl_or_b32 v4, v1, 11, v0
	v_lshl_or_b32 v8, v1, 7, v0
	s_addc_u32 s27, s45, s1
	v_lshl_or_b32 v16, v1, 12, v0
	global_load_dwordx4 v[0:3], v4, s[22:23]
	s_nop 0
	global_load_dwordx4 v[4:7], v4, s[22:23] offset:128
	s_nop 0
	global_load_dwordx4 v[8:11], v8, s[26:27]
	s_nop 0
	global_load_dwordx4 v[12:15], v16, s[24:25]
	s_lshr_b32 s58, s17, 6
	s_add_u32 s34, s24, 0x40000
	s_addc_u32 s35, s25, 0
	global_load_dwordx4 v[16:19], v16, s[34:35]
	v_mov_b32_e32 v22, v199
	v_mad_u32_u24 v23, v20, s51, 0
	v_lshrrev_b32_e32 v24, 3, v22
	v_lshlrev_b32_e32 v25, 4, v22
	v_lshlrev_b32_e32 v22, 3, v22
	v_mul_lo_u32 v26, v24, s51
	v_mul_lo_u32 v24, v24, s5
	v_and_b32_e32 v27, 0x70, v25
	v_and_b32_e32 v25, 0x60, v25
	v_and_b32_e32 v22, 8, v22
	v_add_u32_e32 v24, 0, v24
	v_add3_u32 v26, 0, v26, v27
	v_add3_u32 v22, v24, v25, v22
	s_or_b32 s59, s57, 31
	v_add_u32_e32 v24, 0x6000, v22
	v_add_u32_e32 v22, 0x8800, v22
	s_add_i32 s61, s58, -1
	s_add_u32 s28, s0, 0x12902000
	v_mov_b32_e32 v48, v181
	v_mov_b32_e32 v49, v181
	v_mov_b32_e32 v62, v181
	v_mov_b32_e32 v63, v181
	v_lshlrev_b32_e32 v198, 3, v21
	v_lshlrev_b32_e32 v197, 2, v21
	s_addc_u32 s29, s1, 0
	s_or_b32 s18, s18, s16
	v_mov_b32_e32 v50, v181
	v_mov_b32_e32 v51, v181
	v_mov_b32_e32 v52, v181
	v_mov_b32_e32 v53, v181
	v_mov_b32_e32 v54, v181
	v_mov_b32_e32 v55, v181
	v_mov_b32_e32 v56, v181
	v_mov_b32_e32 v57, v181
	v_mov_b32_e32 v58, v181
	v_mov_b32_e32 v59, v181
	v_mov_b32_e32 v60, v181
	v_mov_b32_e32 v61, v181
	v_add_u32_e32 v205, v23, v180
	v_mov_b64_e32 v[32:33], v[48:49]
	v_mov_b64_e32 v[78:79], v[62:63]
	s_waitcnt vmcnt(4)
	ds_write_b128 v26, v[0:3]
	s_waitcnt vmcnt(3)
	ds_write_b128 v26, v[4:7] offset:128
	s_waitcnt vmcnt(2)
	ds_write_b128 v26, v[8:11] offset:256
	s_waitcnt vmcnt(1)
	ds_write2_b64 v24, v[12:13], v[14:15] offset0:128 offset1:130
	s_waitcnt vmcnt(0)
	ds_write2_b64 v22, v[16:17], v[18:19] offset1:2
	v_lshlrev_b32_e32 v0, 8, v20
	v_mov_b32_e32 v1, s63
	v_sub_u32_e32 v0, v23, v0
	v_mad_u32_u24 v1, v20, s5, v1
	v_add_u32_e32 v207, v0, v180
	v_add_u32_e32 v208, v1, v180
	v_mov_b64_e32 v[16:17], v[48:49]
	v_mov_b64_e32 v[0:1], v[48:49]
	s_mov_b32 s60, 2
	v_mov_b32_e32 v206, 0
	s_mov_b32 s62, 63
	s_mov_b64 s[0:1], s[18:19]
	s_mov_b64 s[36:37], s[28:29]
	s_mov_b64 s[38:39], s[20:21]
	v_mov_b64_e32 v[34:35], v[50:51]
	v_mov_b64_e32 v[36:37], v[52:53]
	v_mov_b64_e32 v[38:39], v[54:55]
	v_mov_b64_e32 v[40:41], v[56:57]
	v_mov_b64_e32 v[42:43], v[58:59]
	v_mov_b64_e32 v[44:45], v[60:61]
	v_mov_b64_e32 v[46:47], v[62:63]
	v_mov_b64_e32 v[18:19], v[50:51]
	v_mov_b64_e32 v[20:21], v[52:53]
	v_mov_b64_e32 v[22:23], v[54:55]
	v_mov_b64_e32 v[24:25], v[56:57]
	v_mov_b64_e32 v[26:27], v[58:59]
	v_mov_b64_e32 v[28:29], v[60:61]
	v_mov_b64_e32 v[30:31], v[62:63]
	v_mov_b64_e32 v[2:3], v[50:51]
	v_mov_b64_e32 v[4:5], v[52:53]
	v_mov_b64_e32 v[6:7], v[54:55]
	v_mov_b64_e32 v[8:9], v[56:57]
	v_mov_b64_e32 v[10:11], v[58:59]
	v_mov_b64_e32 v[12:13], v[60:61]
	v_mov_b64_e32 v[14:15], v[62:63]
	v_mov_b32_e32 v209, 0
	v_mov_b64_e32 v[76:77], v[60:61]
	v_mov_b64_e32 v[74:75], v[58:59]
	v_mov_b64_e32 v[72:73], v[56:57]
	v_mov_b64_e32 v[70:71], v[54:55]
	v_mov_b64_e32 v[68:69], v[52:53]
	v_mov_b64_e32 v[66:67], v[50:51]
	v_mov_b64_e32 v[64:65], v[48:49]
	v_mov_b32_e32 v80, v199
	s_add_u32 s98, s6, s0
	v_lshrrev_b32_e32 v81, 3, v80
	v_lshlrev_b32_e32 v80, 4, v80
	v_and_b32_e32 v80, 0x70, v80
	v_lshl_or_b32 v180, v81, 11, v80
	s_addc_u32 s99, s7, s1
	v_lshl_add_u64 v[82:83], s[98:99], 0, v[180:181]
	v_add_co_u32_e32 v82, vcc, s53, v82
	s_add_u32 s98, s6, s36
	s_nop 0
	v_addc_co_u32_e32 v83, vcc, 0, v83, vcc
	s_addc_u32 s99, s7, s37
	v_lshl_or_b32 v84, v81, 7, v80
	global_load_dwordx4 v[160:163], v[82:83], off
	global_load_dwordx4 v[164:167], v84, s[98:99]
	s_add_u32 s98, s6, s38
	v_lshl_or_b32 v80, v81, 12, v80
	v_mov_b32_e32 v81, v181
	s_addc_u32 s99, s7, s39
	v_lshl_add_u64 v[80:81], s[98:99], 0, v[80:81]
	v_add_co_u32_e32 v84, vcc, 0xe900000, v80
	s_nop 0
	v_addc_co_u32_e32 v85, vcc, 0, v81, vcc
	v_add_co_u32_e32 v80, vcc, 0xe940000, v80
	global_load_dwordx4 v[176:179], v[82:83], off offset:128
	global_load_dwordx4 v[168:171], v[84:85], off offset:128
	v_addc_co_u32_e32 v81, vcc, 0, v81, vcc
	global_load_dwordx4 v[172:175], v[80:81], off offset:128
	s_waitcnt lgkmcnt(0)
	s_barrier
	s_branch .LBB0_940
.LBB0_939:
	s_add_i32 s60, s60, 2
	s_addk_i32 s62, 0x80
	s_add_u32 s38, s38, 0x100
	s_addc_u32 s39, s39, 0
	s_add_u32 s36, s36, 0x4000
	s_addc_u32 s37, s37, 0
	s_add_u32 s0, s0, 0x40000
	s_addc_u32 s1, s1, 0
	s_and_b64 vcc, exec, s[10:11]
	s_cbranch_vccnz .Lah_skip_1
	v_mov_b32_e32 v80, v199
	s_add_u32 s98, s6, s0
	v_lshrrev_b32_e32 v81, 3, v80
	v_lshlrev_b32_e32 v80, 4, v80
	v_and_b32_e32 v80, 0x70, v80
	v_lshl_or_b32 v180, v81, 11, v80
	s_addc_u32 s99, s7, s1
	v_lshl_add_u64 v[82:83], s[98:99], 0, v[180:181]
	v_add_co_u32_e32 v82, vcc, s53, v82
	s_add_u32 s98, s6, s36
	s_nop 0
	v_addc_co_u32_e32 v83, vcc, 0, v83, vcc
	s_addc_u32 s99, s7, s37
	v_lshl_or_b32 v84, v81, 7, v80
	global_load_dwordx4 v[160:163], v[82:83], off
	global_load_dwordx4 v[164:167], v84, s[98:99]
	s_add_u32 s98, s6, s38
	v_lshl_or_b32 v80, v81, 12, v80
	v_mov_b32_e32 v81, v181
	s_addc_u32 s99, s7, s39
	v_lshl_add_u64 v[80:81], s[98:99], 0, v[80:81]
	v_add_co_u32_e32 v84, vcc, 0xe900000, v80
	s_nop 0
	v_addc_co_u32_e32 v85, vcc, 0, v81, vcc
	v_add_co_u32_e32 v80, vcc, 0xe940000, v80
	global_load_dwordx4 v[176:179], v[82:83], off offset:128
	global_load_dwordx4 v[168:171], v[84:85], off offset:128
	v_addc_co_u32_e32 v81, vcc, 0, v81, vcc
	global_load_dwordx4 v[172:175], v[80:81], off offset:128
.Lah_skip_1:
	s_andn2_b64 vcc, exec, s[10:11]
	s_waitcnt lgkmcnt(0)
	s_barrier
	s_cbranch_vccz .LBB0_960
.LBB0_940:
	s_sub_i32 s10, s62, 63
	s_cmp_gt_i32 s10, s59
	s_cbranch_scc1 .LBB0_951
	ds_read_b128 v[80:83], v205
	ds_read_b128 v[210:213], v205 offset:32
	ds_read_b128 v[214:217], v205 offset:12800
	ds_read_b128 v[220:223], v205 offset:12832
	s_waitcnt lgkmcnt(3)
	v_mfma_f32_32x32x16_bf16 v[96:111], v[80:83], v[112:115], v[64:79]
	s_waitcnt lgkmcnt(1)
	v_mfma_f32_32x32x16_bf16 v[80:95], v[214:217], v[112:115], v[64:79]
	ds_read_b128 v[214:217], v205 offset:64
	ds_read_b128 v[224:227], v205 offset:12864
	v_mfma_f32_32x32x16_bf16 v[96:111], v[210:213], v[116:119], v[96:111]
	s_waitcnt lgkmcnt(2)
	v_mfma_f32_32x32x16_bf16 v[80:95], v[220:223], v[116:119], v[80:95]
	ds_read_b128 v[210:213], v205 offset:96
	ds_read_b128 v[220:223], v205 offset:12896
	s_waitcnt lgkmcnt(3)
	v_mfma_f32_32x32x16_bf16 v[96:111], v[214:217], v[120:123], v[96:111]
	s_waitcnt lgkmcnt(2)
	v_mfma_f32_32x32x16_bf16 v[80:95], v[224:227], v[120:123], v[80:95]
	ds_read_b128 v[214:217], v205 offset:128
	ds_read_b128 v[224:227], v205 offset:12928
	s_waitcnt lgkmcnt(3)
	v_mfma_f32_32x32x16_bf16 v[96:111], v[210:213], v[124:127], v[96:111]
	s_waitcnt lgkmcnt(2)
	v_mfma_f32_32x32x16_bf16 v[80:95], v[220:223], v[124:127], v[80:95]
	ds_read_b128 v[210:213], v205 offset:160
	ds_read_b128 v[220:223], v205 offset:12960
	s_waitcnt lgkmcnt(3)
	v_mfma_f32_32x32x16_bf16 v[96:111], v[214:217], v[128:131], v[96:111]
	s_waitcnt lgkmcnt(2)
	v_mfma_f32_32x32x16_bf16 v[80:95], v[224:227], v[128:131], v[80:95]
	ds_read_b128 v[214:217], v205 offset:192
	ds_read_b128 v[224:227], v205 offset:12992
	s_waitcnt lgkmcnt(3)
	v_mfma_f32_32x32x16_bf16 v[96:111], v[210:213], v[132:135], v[96:111]
	s_waitcnt lgkmcnt(2)
	v_mfma_f32_32x32x16_bf16 v[80:95], v[220:223], v[132:135], v[80:95]
	ds_read_b128 v[210:213], v205 offset:224
	ds_read_b128 v[220:223], v205 offset:13024
	s_waitcnt lgkmcnt(3)
	v_mfma_f32_32x32x16_bf16 v[96:111], v[214:217], v[136:139], v[96:111]
	s_waitcnt lgkmcnt(2)
	v_mfma_f32_32x32x16_bf16 v[80:95], v[224:227], v[136:139], v[80:95]
	ds_read_b128 v[214:217], v205 offset:256
	ds_read_b128 v[224:227], v205 offset:13056
	s_waitcnt lgkmcnt(3)
	v_mfma_f32_32x32x16_bf16 v[96:111], v[210:213], v[140:143], v[96:111]
	s_waitcnt lgkmcnt(2)
	v_mfma_f32_32x32x16_bf16 v[80:95], v[220:223], v[140:143], v[80:95]
	ds_read_b128 v[210:213], v205 offset:288
	ds_read_b128 v[220:223], v205 offset:13088
	s_waitcnt lgkmcnt(3)
	v_mfma_f32_32x32x16_bf16 v[96:111], v[214:217], v[144:147], v[96:111]
	s_waitcnt lgkmcnt(2)
	v_mfma_f32_32x32x16_bf16 v[80:95], v[224:227], v[144:147], v[80:95]
	ds_read_b128 v[214:217], v205 offset:320
	ds_read_b128 v[224:227], v205 offset:13120
	s_waitcnt lgkmcnt(3)
	v_mfma_f32_32x32x16_bf16 v[96:111], v[210:213], v[148:151], v[96:111]
	s_waitcnt lgkmcnt(2)
	v_mfma_f32_32x32x16_bf16 v[80:95], v[220:223], v[148:151], v[80:95]
	ds_read_b128 v[210:213], v205 offset:352
	ds_read_b128 v[220:223], v205 offset:13152
	s_waitcnt lgkmcnt(3)
	v_mfma_f32_32x32x16_bf16 v[96:111], v[214:217], v[152:155], v[96:111]
	s_waitcnt lgkmcnt(2)
	v_mfma_f32_32x32x16_bf16 v[80:95], v[224:227], v[152:155], v[80:95]
	s_waitcnt lgkmcnt(1)
	v_mfma_f32_32x32x16_bf16 v[96:111], v[210:213], v[156:159], v[96:111]
	s_waitcnt lgkmcnt(0)
	v_mfma_f32_32x32x16_bf16 v[80:95], v[220:223], v[156:159], v[80:95]
	s_cmp_le_i32 s62, s57
	s_nop 15
	s_nop 7
	s_cbranch_scc1 .LBB0_943
	v_add_u32_e32 v180, s62, v197
	v_subrev_u32_e32 v203, 31, v180
	v_subrev_u32_e32 v202, 63, v180
	v_cmp_le_i32_e32 vcc, v203, v196
	s_nop 5
	v_cndmask_b32_e32 v80, v204, v80, vcc
	v_cmp_lt_i32_e32 vcc, v202, v196
	s_nop 1
	v_cndmask_b32_e32 v97, v204, v97, vcc
	v_cmp_le_i32_e32 vcc, v202, v196
	v_subrev_u32_e32 v202, 30, v180
	s_nop 0
	v_cndmask_b32_e32 v96, v204, v96, vcc
	v_cmp_le_i32_e32 vcc, v202, v196
	v_subrev_u32_e32 v202, 61, v180
	s_nop 0
	v_cndmask_b32_e32 v81, v204, v81, vcc
	v_cmp_le_i32_e32 vcc, v202, v196
	v_subrev_u32_e32 v202, 29, v180
	s_nop 0
	v_cndmask_b32_e32 v98, v204, v98, vcc
	v_cmp_le_i32_e32 vcc, v202, v196
	v_subrev_u32_e32 v202, 60, v180
	s_nop 0
	v_cndmask_b32_e32 v82, v204, v82, vcc
	v_cmp_le_i32_e32 vcc, v202, v196
	v_subrev_u32_e32 v202, 28, v180
	s_nop 0
	v_cndmask_b32_e32 v99, v204, v99, vcc
	v_cmp_le_i32_e32 vcc, v202, v196
	v_subrev_u32_e32 v202, 55, v180
	s_nop 0
	v_cndmask_b32_e32 v83, v204, v83, vcc
	v_cmp_le_i32_e32 vcc, v202, v196
	v_subrev_u32_e32 v202, 23, v180
	s_nop 0
	v_cndmask_b32_e32 v100, v204, v100, vcc
	v_cmp_le_i32_e32 vcc, v202, v196
	v_subrev_u32_e32 v202, 54, v180
	s_nop 0
	v_cndmask_b32_e32 v84, v204, v84, vcc
	v_cmp_le_i32_e32 vcc, v202, v196
	v_subrev_u32_e32 v202, 22, v180
	s_nop 0
	v_cndmask_b32_e32 v101, v204, v101, vcc
	v_cmp_le_i32_e32 vcc, v202, v196
	v_subrev_u32_e32 v202, 53, v180
	s_nop 0
	v_cndmask_b32_e32 v85, v204, v85, vcc
	v_cmp_le_i32_e32 vcc, v202, v196
	v_subrev_u32_e32 v202, 21, v180
	s_nop 0
	v_cndmask_b32_e32 v102, v204, v102, vcc
	v_cmp_le_i32_e32 vcc, v202, v196
	v_subrev_u32_e32 v202, 52, v180
	s_nop 0
	v_cndmask_b32_e32 v86, v204, v86, vcc
	v_cmp_le_i32_e32 vcc, v202, v196
	v_subrev_u32_e32 v202, 20, v180
	s_nop 0
	v_cndmask_b32_e32 v103, v204, v103, vcc
	v_cmp_le_i32_e32 vcc, v202, v196
	v_subrev_u32_e32 v202, 47, v180
	s_nop 0
	v_cndmask_b32_e32 v87, v204, v87, vcc
	v_cmp_le_i32_e32 vcc, v202, v196
	v_add_u32_e32 v202, -15, v180
	s_nop 0
	v_cndmask_b32_e32 v104, v204, v104, vcc
	v_cmp_le_i32_e32 vcc, v202, v196
	v_subrev_u32_e32 v202, 46, v180
	s_nop 0
	v_cndmask_b32_e32 v88, v204, v88, vcc
	v_cmp_le_i32_e32 vcc, v202, v196
	v_add_u32_e32 v202, -14, v180
	s_nop 0
	v_cndmask_b32_e32 v105, v204, v105, vcc
	v_cmp_le_i32_e32 vcc, v202, v196
	v_subrev_u32_e32 v202, 45, v180
	s_nop 0
	v_cndmask_b32_e32 v89, v204, v89, vcc
	v_cmp_le_i32_e32 vcc, v202, v196
	v_add_u32_e32 v202, -13, v180
	s_nop 0
	v_cndmask_b32_e32 v106, v204, v106, vcc
	v_cmp_le_i32_e32 vcc, v202, v196
	v_subrev_u32_e32 v202, 44, v180
	s_nop 0
	v_cndmask_b32_e32 v90, v204, v90, vcc
	v_cmp_le_i32_e32 vcc, v202, v196
	v_add_u32_e32 v202, -12, v180
	s_nop 0
	v_cndmask_b32_e32 v107, v204, v107, vcc
	v_cmp_le_i32_e32 vcc, v202, v196
	v_subrev_u32_e32 v202, 39, v180
	s_nop 0
	v_cndmask_b32_e32 v91, v204, v91, vcc
	v_cmp_le_i32_e32 vcc, v202, v196
	v_add_u32_e32 v202, -7, v180
	s_nop 0
	v_cndmask_b32_e32 v108, v204, v108, vcc
	v_cmp_le_i32_e32 vcc, v202, v196
	v_subrev_u32_e32 v202, 38, v180
	s_nop 0
	v_cndmask_b32_e32 v92, v204, v92, vcc
	v_cmp_le_i32_e32 vcc, v202, v196
	v_add_u32_e32 v202, -6, v180
	s_nop 0
	v_cndmask_b32_e32 v109, v204, v109, vcc
	v_cmp_le_i32_e32 vcc, v202, v196
	v_subrev_u32_e32 v202, 37, v180
	s_nop 0
	v_cndmask_b32_e32 v93, v204, v93, vcc
	v_cmp_le_i32_e32 vcc, v202, v196
	v_add_u32_e32 v202, -5, v180
	s_nop 0
	v_cndmask_b32_e32 v110, v204, v110, vcc
	v_cmp_le_i32_e32 vcc, v202, v196
	v_subrev_u32_e32 v202, 36, v180
	v_add_u32_e32 v180, -4, v180
	v_cndmask_b32_e32 v94, v204, v94, vcc
	v_cmp_le_i32_e32 vcc, v202, v196
	s_nop 1
	v_cndmask_b32_e32 v111, v204, v111, vcc
	v_cmp_le_i32_e32 vcc, v180, v196
	s_nop 1
	v_cndmask_b32_e32 v95, v204, v95, vcc

.LBB0_960:
	v_and_b32_e32 v65, 64, v219
	v_xor_b32_e32 v64, 32, v219
	v_add_u32_e32 v65, 64, v65
	v_cmp_lt_i32_e32 vcc, v64, v65
	v_lshlrev_b32_e32 v180, 1, v198
	s_lshl_b32 s64, s52, 1
	v_cndmask_b32_e32 v64, v219, v64, vcc
	v_lshlrev_b32_e32 v205, 2, v64
	v_mov_b32_e32 v64, v206
	v_mov_b32_e32 v251, v206
	s_nop 1
	v_permlane32_swap_b32_e32 v64, v251
	v_readlane_b32 s58, v255, 3
	v_readlane_b32 s60, v253, 16
	s_mov_b32 s36, 2
	s_mov_b32 s40, 63
	s_waitcnt lgkmcnt(0)
	v_add_f32_e32 v66, v64, v251
	v_div_scale_f32 v67, s[0:1], v66, v66, 1.0
	v_rcp_f32_e32 v68, v67
	v_div_scale_f32 v69, vcc, 1.0, v66, 1.0
	v_lshlrev_b64 v[64:65], 11, v[194:195]
	v_fma_f32 v70, -v67, v68, 1.0
	v_fmac_f32_e32 v68, v70, v68
	v_mul_f32_e32 v70, v69, v68
	v_fma_f32 v71, -v67, v70, v69
	v_fmac_f32_e32 v70, v71, v68
	v_fma_f32 v67, -v67, v70, v69
	v_div_fmas_f32 v67, v67, v68, v70
	v_div_fixup_f32 v66, v67, v66, 1.0
	v_pk_mul_f32 v[48:49], v[48:49], v[66:67] op_sel_hi:[1,0]
	v_pk_mul_f32 v[50:51], v[50:51], v[66:67] op_sel_hi:[1,0]
	v_pk_mul_f32 v[32:33], v[32:33], v[66:67] op_sel_hi:[1,0]
	v_pk_mul_f32 v[34:35], v[34:35], v[66:67] op_sel_hi:[1,0]
	v_pk_mul_f32 v[16:17], v[16:17], v[66:67] op_sel_hi:[1,0]
	v_pk_mul_f32 v[18:19], v[18:19], v[66:67] op_sel_hi:[1,0]
	v_pk_mul_f32 v[0:1], v[0:1], v[66:67] op_sel_hi:[1,0]
	v_pk_mul_f32 v[2:3], v[2:3], v[66:67] op_sel_hi:[1,0]
	v_lshl_add_u64 v[64:65], s[14:15], 0, v[64:65]
	s_lshl_b32 s0, s56, 1
	s_mov_b32 s1, s65
	v_cvt_pk_bf16_f32 v48, v48, v49
	v_cvt_pk_bf16_f32 v49, v50, v51
	v_pk_mul_f32 v[50:51], v[52:53], v[66:67] op_sel_hi:[1,0]
	v_pk_mul_f32 v[52:53], v[54:55], v[66:67] op_sel_hi:[1,0]
	v_cvt_pk_bf16_f32 v32, v32, v33
	v_cvt_pk_bf16_f32 v33, v34, v35
	v_pk_mul_f32 v[34:35], v[36:37], v[66:67] op_sel_hi:[1,0]
	v_pk_mul_f32 v[36:37], v[38:39], v[66:67] op_sel_hi:[1,0]
	v_cvt_pk_bf16_f32 v16, v16, v17
	v_cvt_pk_bf16_f32 v17, v18, v19
	v_pk_mul_f32 v[18:19], v[20:21], v[66:67] op_sel_hi:[1,0]
	v_pk_mul_f32 v[20:21], v[22:23], v[66:67] op_sel_hi:[1,0]
	v_cvt_pk_bf16_f32 v0, v0, v1
	v_cvt_pk_bf16_f32 v1, v2, v3
	v_pk_mul_f32 v[2:3], v[4:5], v[66:67] op_sel_hi:[1,0]
	v_pk_mul_f32 v[4:5], v[6:7], v[66:67] op_sel_hi:[1,0]
	v_lshl_add_u64 v[64:65], v[64:65], 0, s[0:1]
	v_cvt_pk_bf16_f32 v50, v50, v51
	v_cvt_pk_bf16_f32 v51, v52, v53
	v_cvt_pk_bf16_f32 v34, v34, v35
	v_cvt_pk_bf16_f32 v35, v36, v37
	v_cvt_pk_bf16_f32 v18, v18, v19
	v_cvt_pk_bf16_f32 v19, v20, v21
	v_cvt_pk_bf16_f32 v2, v2, v3
	v_cvt_pk_bf16_f32 v3, v4, v5
	v_lshl_add_u64 v[64:65], v[64:65], 0, v[180:181]
	v_permlane32_swap_b32_e32 v48, v50
	v_permlane32_swap_b32_e32 v49, v51
	v_permlane32_swap_b32_e32 v32, v34
	v_permlane32_swap_b32_e32 v33, v35
	v_permlane32_swap_b32_e32 v16, v18
	v_permlane32_swap_b32_e32 v17, v19
	v_permlane32_swap_b32_e32 v0, v2
	v_permlane32_swap_b32_e32 v1, v3
	global_store_dwordx4 v[64:65], v[48:51], off
	global_store_dwordx4 v[64:65], v[32:35], off offset:64
	global_store_dwordx4 v[64:65], v[16:19], off offset:128
	v_pk_mul_f32 v[48:49], v[56:57], v[66:67] op_sel_hi:[1,0]
	v_pk_mul_f32 v[50:51], v[58:59], v[66:67] op_sel_hi:[1,0]
	v_pk_mul_f32 v[32:33], v[40:41], v[66:67] op_sel_hi:[1,0]
	v_pk_mul_f32 v[34:35], v[42:43], v[66:67] op_sel_hi:[1,0]
	v_pk_mul_f32 v[16:17], v[24:25], v[66:67] op_sel_hi:[1,0]
	v_pk_mul_f32 v[18:19], v[26:27], v[66:67] op_sel_hi:[1,0]
	global_store_dwordx4 v[64:65], v[0:3], off offset:192
	v_cvt_pk_bf16_f32 v48, v48, v49
	v_cvt_pk_bf16_f32 v49, v50, v51
	v_pk_mul_f32 v[0:1], v[8:9], v[66:67] op_sel_hi:[1,0]
	v_pk_mul_f32 v[2:3], v[10:11], v[66:67] op_sel_hi:[1,0]
	v_pk_mul_f32 v[50:51], v[60:61], v[66:67] op_sel_hi:[1,0]
	v_pk_mul_f32 v[52:53], v[62:63], v[66:67] op_sel_hi:[1,0]
	v_cvt_pk_bf16_f32 v32, v32, v33
	v_cvt_pk_bf16_f32 v33, v34, v35
	v_pk_mul_f32 v[34:35], v[44:45], v[66:67] op_sel_hi:[1,0]
	v_pk_mul_f32 v[36:37], v[46:47], v[66:67] op_sel_hi:[1,0]
	v_cvt_pk_bf16_f32 v16, v16, v17
	v_cvt_pk_bf16_f32 v17, v18, v19
	v_pk_mul_f32 v[18:19], v[28:29], v[66:67] op_sel_hi:[1,0]
	v_pk_mul_f32 v[20:21], v[30:31], v[66:67] op_sel_hi:[1,0]
	v_cvt_pk_bf16_f32 v0, v0, v1
	v_cvt_pk_bf16_f32 v1, v2, v3
	v_pk_mul_f32 v[2:3], v[12:13], v[66:67] op_sel_hi:[1,0]
	v_pk_mul_f32 v[4:5], v[14:15], v[66:67] op_sel_hi:[1,0]
	v_cvt_pk_bf16_f32 v50, v50, v51
	v_cvt_pk_bf16_f32 v51, v52, v53
	v_cvt_pk_bf16_f32 v34, v34, v35
	v_cvt_pk_bf16_f32 v35, v36, v37
	v_cvt_pk_bf16_f32 v18, v18, v19
	v_cvt_pk_bf16_f32 v19, v20, v21
	v_cvt_pk_bf16_f32 v2, v2, v3
	v_cvt_pk_bf16_f32 v3, v4, v5
	v_permlane32_swap_b32_e32 v48, v50
	v_permlane32_swap_b32_e32 v49, v51
	v_permlane32_swap_b32_e32 v32, v34
	v_permlane32_swap_b32_e32 v33, v35
	v_permlane32_swap_b32_e32 v16, v18
	v_permlane32_swap_b32_e32 v17, v19
	v_permlane32_swap_b32_e32 v0, v2
	v_permlane32_swap_b32_e32 v1, v3
	v_mov_b32_e32 v195, v218
	global_store_dwordx4 v[64:65], v[48:51], off offset:32
	global_store_dwordx4 v[64:65], v[32:35], off offset:96
	global_store_dwordx4 v[64:65], v[16:19], off offset:160
	global_store_dwordx4 v[64:65], v[0:3], off offset:224
	v_mov_b32_e32 v48, v181
	v_readfirstlane_b32 s1, v195
	s_ashr_i32 s1, s1, 1
	s_andn2_b32 s1, s1, 31
	v_and_b32_e32 v20, 31, v195
	s_add_i32 s1, s1, s49
	v_or_b32_e32 v198, s1, v20
	v_ashrrev_i32_e32 v199, 31, v198
	v_lshl_add_u64 v[196:197], s[30:31], 0, v[198:199]
	v_mov_b64_e32 v[0:1], s[8:9]
	v_mad_u64_u32 v[0:1], s[10:11], v196, s50, v[0:1]
	v_bfe_u32 v21, v195, 5, 1
	v_mad_i32_i24 v1, v197, s50, v1
	v_lshl_add_u64 v[0:1], v[0:1], 0, s[64:65]
	v_lshlrev_b32_e32 v180, 4, v21
	v_lshl_add_u64 v[0:1], v[0:1], 0, v[180:181]
	global_load_dwordx4 v[112:115], v[0:1], off
	global_load_dwordx4 v[116:119], v[0:1], off offset:32
	global_load_dwordx4 v[120:123], v[0:1], off offset:64
	global_load_dwordx4 v[124:127], v[0:1], off offset:96
	global_load_dwordx4 v[128:131], v[0:1], off offset:128
	global_load_dwordx4 v[132:135], v[0:1], off offset:160
	global_load_dwordx4 v[136:139], v[0:1], off offset:192
	global_load_dwordx4 v[140:143], v[0:1], off offset:224
	global_load_dwordx4 v[144:147], v[0:1], off offset:256
	global_load_dwordx4 v[148:151], v[0:1], off offset:288
	global_load_dwordx4 v[152:155], v[0:1], off offset:320
	global_load_dwordx4 v[156:159], v[0:1], off offset:352
	v_mov_b32_e32 v0, v195
	v_mov_b32_e32 v22, v195
	v_lshrrev_b32_e32 v12, 3, v0
	v_lshlrev_b32_e32 v0, 4, v0
	v_and_b32_e32 v13, 0x70, v0
	v_lshl_or_b32 v4, v12, 11, v13
	v_lshl_or_b32 v8, v12, 7, v13
	global_load_dwordx4 v[0:3], v4, s[22:23]
	s_nop 0
	global_load_dwordx4 v[4:7], v4, s[22:23] offset:128
	s_nop 0
	global_load_dwordx4 v[8:11], v8, s[26:27]
	v_lshl_or_b32 v16, v12, 12, v13
	global_load_dwordx4 v[12:15], v16, s[24:25]
	s_nop 0
	global_load_dwordx4 v[16:19], v16, s[34:35]
	s_addk_i32 s49, 0x100
	v_lshrrev_b32_e32 v23, 3, v22
	v_lshlrev_b32_e32 v25, 4, v22
	v_mul_lo_u32 v24, v23, s51
	v_and_b32_e32 v26, 0x70, v25
	v_mul_lo_u32 v23, v23, s5
	v_lshlrev_b32_e32 v22, 3, v22
	v_add3_u32 v24, 0, v24, v26
	v_and_b32_e32 v25, 0x60, v25
	v_and_b32_e32 v22, 8, v22
	s_waitcnt vmcnt(4)
	ds_write_b128 v24, v[0:3]
	s_waitcnt vmcnt(3)
	ds_write_b128 v24, v[4:7] offset:128
	s_waitcnt vmcnt(2)
	ds_write_b128 v24, v[8:11] offset:256
	v_add_u32_e32 v0, 0, v23
	v_add3_u32 v0, v0, v25, v22
	v_add_u32_e32 v1, 0x6000, v0
	v_add_u32_e32 v0, 0x8800, v0
	s_waitcnt vmcnt(1)
	ds_write2_b64 v1, v[12:13], v[14:15] offset0:128 offset1:130
	s_waitcnt vmcnt(0)
	ds_write2_b64 v0, v[16:17], v[18:19] offset1:2
	v_mad_u32_u24 v0, v20, s51, 0
	v_lshlrev_b32_e32 v1, 8, v20
	v_mov_b32_e32 v2, s63
	v_sub_u32_e32 v1, v0, v1
	v_mad_u32_u24 v2, v20, s5, v2
	v_mov_b32_e32 v49, v181
	v_mov_b32_e32 v62, v181
	v_mov_b32_e32 v63, v181
	v_lshlrev_b32_e32 v194, 3, v21
	s_lshr_b32 s37, s49, 6
	v_lshlrev_b32_e32 v199, 2, v21
	v_mov_b32_e32 v50, v181
	v_mov_b32_e32 v51, v181
	v_mov_b32_e32 v52, v181
	v_mov_b32_e32 v53, v181
	v_mov_b32_e32 v54, v181
	v_mov_b32_e32 v55, v181
	v_mov_b32_e32 v56, v181
	v_mov_b32_e32 v57, v181
	v_mov_b32_e32 v58, v181
	v_mov_b32_e32 v59, v181
	v_mov_b32_e32 v60, v181
	v_mov_b32_e32 v61, v181
	v_add_u32_e32 v207, v0, v180
	v_add_u32_e32 v208, v1, v180
	v_add_u32_e32 v209, v2, v180
	v_mov_b64_e32 v[32:33], v[48:49]
	v_mov_b64_e32 v[16:17], v[48:49]
	v_mov_b64_e32 v[0:1], v[48:49]
	v_mov_b64_e32 v[78:79], v[62:63]
	v_readlane_b32 s56, v255, 1
	s_or_b32 s38, s1, 31
	s_add_i32 s39, s37, -1
	v_mov_b32_e32 v206, 0
	v_mov_b64_e32 v[34:35], v[50:51]
	v_mov_b64_e32 v[36:37], v[52:53]
	v_mov_b64_e32 v[38:39], v[54:55]
	v_mov_b64_e32 v[40:41], v[56:57]
	v_mov_b64_e32 v[42:43], v[58:59]
	v_mov_b64_e32 v[44:45], v[60:61]
	v_mov_b64_e32 v[46:47], v[62:63]
	v_mov_b64_e32 v[18:19], v[50:51]
	v_mov_b64_e32 v[20:21], v[52:53]
	v_mov_b64_e32 v[22:23], v[54:55]
	v_mov_b64_e32 v[24:25], v[56:57]
	v_mov_b64_e32 v[26:27], v[58:59]
	v_mov_b64_e32 v[28:29], v[60:61]
	v_mov_b64_e32 v[30:31], v[62:63]
	v_mov_b64_e32 v[2:3], v[50:51]
	v_mov_b64_e32 v[4:5], v[52:53]
	v_mov_b64_e32 v[6:7], v[54:55]
	v_mov_b64_e32 v[8:9], v[56:57]
	v_mov_b64_e32 v[10:11], v[58:59]
	v_mov_b64_e32 v[12:13], v[60:61]
	v_mov_b64_e32 v[14:15], v[62:63]
	v_mov_b32_e32 v210, 0
	v_mov_b64_e32 v[76:77], v[60:61]
	v_mov_b64_e32 v[74:75], v[58:59]
	v_mov_b64_e32 v[72:73], v[56:57]
	v_mov_b64_e32 v[70:71], v[54:55]
	v_mov_b64_e32 v[68:69], v[52:53]
	v_mov_b64_e32 v[66:67], v[50:51]
	v_mov_b64_e32 v[64:65], v[48:49]
	v_readlane_b32 s57, v255, 2
	v_readlane_b32 s59, v255, 4
	v_readlane_b32 s61, v253, 17
	v_mov_b32_e32 v80, v195
	s_add_u32 s98, s6, s18
	v_lshrrev_b32_e32 v81, 3, v80
	v_lshlrev_b32_e32 v80, 4, v80
	v_and_b32_e32 v80, 0x70, v80
	v_lshl_or_b32 v180, v81, 11, v80
	s_addc_u32 s99, s7, s19
	v_lshl_add_u64 v[82:83], s[98:99], 0, v[180:181]
	v_add_co_u32_e32 v82, vcc, s53, v82
	s_add_u32 s98, s6, s28
	s_nop 0
	v_addc_co_u32_e32 v83, vcc, 0, v83, vcc
	s_addc_u32 s99, s7, s29
	v_lshl_or_b32 v84, v81, 7, v80
	global_load_dwordx4 v[160:163], v[82:83], off
	global_load_dwordx4 v[164:167], v84, s[98:99]
	s_add_u32 s98, s6, s20
	v_lshl_or_b32 v80, v81, 12, v80
	v_mov_b32_e32 v81, v181
	s_addc_u32 s99, s7, s21
	v_lshl_add_u64 v[80:81], s[98:99], 0, v[80:81]
	v_add_co_u32_e32 v84, vcc, 0xe900000, v80
	s_nop 0
	v_addc_co_u32_e32 v85, vcc, 0, v81, vcc
	v_add_co_u32_e32 v80, vcc, 0xe940000, v80
	global_load_dwordx4 v[176:179], v[82:83], off offset:128
	global_load_dwordx4 v[168:171], v[84:85], off offset:128
	v_addc_co_u32_e32 v81, vcc, 0, v81, vcc
	global_load_dwordx4 v[172:175], v[80:81], off offset:128
	s_waitcnt lgkmcnt(0)
	s_barrier
	s_branch .LBB0_962
.LBB0_961:
	s_add_i32 s36, s36, 2
	s_addk_i32 s40, 0x80
	s_add_u32 s20, s20, 0x100
	s_addc_u32 s21, s21, 0
	s_add_u32 s28, s28, 0x4000
	s_addc_u32 s29, s29, 0
	s_add_u32 s18, s18, 0x40000
	s_addc_u32 s19, s19, 0
	s_and_b64 vcc, exec, s[10:11]
	s_cbranch_vccnz .Lah_skip_2
	v_mov_b32_e32 v80, v195
	s_add_u32 s98, s6, s18
	v_lshrrev_b32_e32 v81, 3, v80
	v_lshlrev_b32_e32 v80, 4, v80
	v_and_b32_e32 v80, 0x70, v80
	v_lshl_or_b32 v180, v81, 11, v80
	s_addc_u32 s99, s7, s19
	v_lshl_add_u64 v[82:83], s[98:99], 0, v[180:181]
	v_add_co_u32_e32 v82, vcc, s53, v82
	s_add_u32 s98, s6, s28
	s_nop 0
	v_addc_co_u32_e32 v83, vcc, 0, v83, vcc
	s_addc_u32 s99, s7, s29
	v_lshl_or_b32 v84, v81, 7, v80
	global_load_dwordx4 v[160:163], v[82:83], off
	global_load_dwordx4 v[164:167], v84, s[98:99]
	s_add_u32 s98, s6, s20
	v_lshl_or_b32 v80, v81, 12, v80
	v_mov_b32_e32 v81, v181
	s_addc_u32 s99, s7, s21
	v_lshl_add_u64 v[80:81], s[98:99], 0, v[80:81]
	v_add_co_u32_e32 v84, vcc, 0xe900000, v80
	s_nop 0
	v_addc_co_u32_e32 v85, vcc, 0, v81, vcc
	v_add_co_u32_e32 v80, vcc, 0xe940000, v80
	global_load_dwordx4 v[176:179], v[82:83], off offset:128
	global_load_dwordx4 v[168:171], v[84:85], off offset:128
	v_addc_co_u32_e32 v81, vcc, 0, v81, vcc
	global_load_dwordx4 v[172:175], v[80:81], off offset:128

.LBB0_962:
	s_sub_i32 s10, s40, 63
	s_cmp_gt_i32 s10, s38
	s_cbranch_scc1 .LBB0_973
	ds_read_b128 v[80:83], v207
	ds_read_b128 v[212:215], v207 offset:32
	ds_read_b128 v[220:223], v207 offset:12800
	ds_read_b128 v[224:227], v207 offset:12832
	s_waitcnt lgkmcnt(3)
	v_mfma_f32_32x32x16_bf16 v[96:111], v[80:83], v[112:115], v[64:79]
	s_waitcnt lgkmcnt(1)
	v_mfma_f32_32x32x16_bf16 v[80:95], v[220:223], v[112:115], v[64:79]
	ds_read_b128 v[220:223], v207 offset:64
	ds_read_b128 v[228:231], v207 offset:12864
	v_mfma_f32_32x32x16_bf16 v[96:111], v[212:215], v[116:119], v[96:111]
	s_waitcnt lgkmcnt(2)
	v_mfma_f32_32x32x16_bf16 v[80:95], v[224:227], v[116:119], v[80:95]
	ds_read_b128 v[212:215], v207 offset:96
	ds_read_b128 v[224:227], v207 offset:12896
	s_waitcnt lgkmcnt(3)
	v_mfma_f32_32x32x16_bf16 v[96:111], v[220:223], v[120:123], v[96:111]
	s_waitcnt lgkmcnt(2)
	v_mfma_f32_32x32x16_bf16 v[80:95], v[228:231], v[120:123], v[80:95]
	ds_read_b128 v[220:223], v207 offset:128
	ds_read_b128 v[228:231], v207 offset:12928
	s_waitcnt lgkmcnt(3)
	v_mfma_f32_32x32x16_bf16 v[96:111], v[212:215], v[124:127], v[96:111]
	s_waitcnt lgkmcnt(2)
	v_mfma_f32_32x32x16_bf16 v[80:95], v[224:227], v[124:127], v[80:95]
	ds_read_b128 v[212:215], v207 offset:160
	ds_read_b128 v[224:227], v207 offset:12960
	s_waitcnt lgkmcnt(3)
	v_mfma_f32_32x32x16_bf16 v[96:111], v[220:223], v[128:131], v[96:111]
	s_waitcnt lgkmcnt(2)
	v_mfma_f32_32x32x16_bf16 v[80:95], v[228:231], v[128:131], v[80:95]
	ds_read_b128 v[220:223], v207 offset:192
	ds_read_b128 v[228:231], v207 offset:12992
	s_waitcnt lgkmcnt(3)
	v_mfma_f32_32x32x16_bf16 v[96:111], v[212:215], v[132:135], v[96:111]
	s_waitcnt lgkmcnt(2)
	v_mfma_f32_32x32x16_bf16 v[80:95], v[224:227], v[132:135], v[80:95]
	ds_read_b128 v[212:215], v207 offset:224
	ds_read_b128 v[224:227], v207 offset:13024
	s_waitcnt lgkmcnt(3)
	v_mfma_f32_32x32x16_bf16 v[96:111], v[220:223], v[136:139], v[96:111]
	s_waitcnt lgkmcnt(2)
	v_mfma_f32_32x32x16_bf16 v[80:95], v[228:231], v[136:139], v[80:95]
	ds_read_b128 v[220:223], v207 offset:256
	ds_read_b128 v[228:231], v207 offset:13056
	s_waitcnt lgkmcnt(3)
	v_mfma_f32_32x32x16_bf16 v[96:111], v[212:215], v[140:143], v[96:111]
	s_waitcnt lgkmcnt(2)
	v_mfma_f32_32x32x16_bf16 v[80:95], v[224:227], v[140:143], v[80:95]
	ds_read_b128 v[212:215], v207 offset:288
	ds_read_b128 v[224:227], v207 offset:13088
	s_waitcnt lgkmcnt(3)
	v_mfma_f32_32x32x16_bf16 v[96:111], v[220:223], v[144:147], v[96:111]
	s_waitcnt lgkmcnt(2)
	v_mfma_f32_32x32x16_bf16 v[80:95], v[228:231], v[144:147], v[80:95]
	ds_read_b128 v[220:223], v207 offset:320
	ds_read_b128 v[228:231], v207 offset:13120
	s_waitcnt lgkmcnt(3)
	v_mfma_f32_32x32x16_bf16 v[96:111], v[212:215], v[148:151], v[96:111]
	s_waitcnt lgkmcnt(2)
	v_mfma_f32_32x32x16_bf16 v[80:95], v[224:227], v[148:151], v[80:95]
	ds_read_b128 v[212:215], v207 offset:352
	ds_read_b128 v[224:227], v207 offset:13152
	s_waitcnt lgkmcnt(3)
	v_mfma_f32_32x32x16_bf16 v[96:111], v[220:223], v[152:155], v[96:111]
	s_waitcnt lgkmcnt(2)
	v_mfma_f32_32x32x16_bf16 v[80:95], v[228:231], v[152:155], v[80:95]
	s_waitcnt lgkmcnt(1)
	v_mfma_f32_32x32x16_bf16 v[96:111], v[212:215], v[156:159], v[96:111]
	s_waitcnt lgkmcnt(0)
	v_mfma_f32_32x32x16_bf16 v[80:95], v[224:227], v[156:159], v[80:95]
	s_cmp_le_i32 s40, s1
	s_nop 15
	s_nop 7
	s_cbranch_scc1 .LBB0_965
	v_add_u32_e32 v180, s40, v199
	v_subrev_u32_e32 v203, 31, v180
	v_subrev_u32_e32 v202, 63, v180
	v_cmp_le_i32_e32 vcc, v203, v198
	s_nop 5
	v_cndmask_b32_e32 v80, v204, v80, vcc
	v_cmp_lt_i32_e32 vcc, v202, v198
	s_nop 1
	v_cndmask_b32_e32 v97, v204, v97, vcc
	v_cmp_le_i32_e32 vcc, v202, v198
	v_subrev_u32_e32 v202, 30, v180
	s_nop 0
	v_cndmask_b32_e32 v96, v204, v96, vcc
	v_cmp_le_i32_e32 vcc, v202, v198
	v_subrev_u32_e32 v202, 61, v180
	s_nop 0
	v_cndmask_b32_e32 v81, v204, v81, vcc
	v_cmp_le_i32_e32 vcc, v202, v198
	v_subrev_u32_e32 v202, 29, v180
	s_nop 0
	v_cndmask_b32_e32 v98, v204, v98, vcc
	v_cmp_le_i32_e32 vcc, v202, v198
	v_subrev_u32_e32 v202, 60, v180
	s_nop 0
	v_cndmask_b32_e32 v82, v204, v82, vcc
	v_cmp_le_i32_e32 vcc, v202, v198
	v_subrev_u32_e32 v202, 28, v180
	s_nop 0
	v_cndmask_b32_e32 v99, v204, v99, vcc
	v_cmp_le_i32_e32 vcc, v202, v198
	v_subrev_u32_e32 v202, 55, v180
	s_nop 0
	v_cndmask_b32_e32 v83, v204, v83, vcc
	v_cmp_le_i32_e32 vcc, v202, v198
	v_subrev_u32_e32 v202, 23, v180
	s_nop 0
	v_cndmask_b32_e32 v100, v204, v100, vcc
	v_cmp_le_i32_e32 vcc, v202, v198
	v_subrev_u32_e32 v202, 54, v180
	s_nop 0
	v_cndmask_b32_e32 v84, v204, v84, vcc
	v_cmp_le_i32_e32 vcc, v202, v198
	v_subrev_u32_e32 v202, 22, v180
	s_nop 0
	v_cndmask_b32_e32 v101, v204, v101, vcc
	v_cmp_le_i32_e32 vcc, v202, v198
	v_subrev_u32_e32 v202, 53, v180
	s_nop 0
	v_cndmask_b32_e32 v85, v204, v85, vcc
	v_cmp_le_i32_e32 vcc, v202, v198
	v_subrev_u32_e32 v202, 21, v180
	s_nop 0
	v_cndmask_b32_e32 v102, v204, v102, vcc
	v_cmp_le_i32_e32 vcc, v202, v198
	v_subrev_u32_e32 v202, 52, v180
	s_nop 0
	v_cndmask_b32_e32 v86, v204, v86, vcc
	v_cmp_le_i32_e32 vcc, v202, v198
	v_subrev_u32_e32 v202, 20, v180
	s_nop 0
	v_cndmask_b32_e32 v103, v204, v103, vcc
	v_cmp_le_i32_e32 vcc, v202, v198
	v_subrev_u32_e32 v202, 47, v180
	s_nop 0
	v_cndmask_b32_e32 v87, v204, v87, vcc
	v_cmp_le_i32_e32 vcc, v202, v198
	v_add_u32_e32 v202, -15, v180
	s_nop 0
	v_cndmask_b32_e32 v104, v204, v104, vcc
	v_cmp_le_i32_e32 vcc, v202, v198
	v_subrev_u32_e32 v202, 46, v180
	s_nop 0
	v_cndmask_b32_e32 v88, v204, v88, vcc
	v_cmp_le_i32_e32 vcc, v202, v198
	v_add_u32_e32 v202, -14, v180
	s_nop 0
	v_cndmask_b32_e32 v105, v204, v105, vcc
	v_cmp_le_i32_e32 vcc, v202, v198
	v_subrev_u32_e32 v202, 45, v180
	s_nop 0
	v_cndmask_b32_e32 v89, v204, v89, vcc
	v_cmp_le_i32_e32 vcc, v202, v198
	v_add_u32_e32 v202, -13, v180
	s_nop 0
	v_cndmask_b32_e32 v106, v204, v106, vcc
	v_cmp_le_i32_e32 vcc, v202, v198
	v_subrev_u32_e32 v202, 44, v180
	s_nop 0
	v_cndmask_b32_e32 v90, v204, v90, vcc
	v_cmp_le_i32_e32 vcc, v202, v198
	v_add_u32_e32 v202, -12, v180
	s_nop 0
	v_cndmask_b32_e32 v107, v204, v107, vcc
	v_cmp_le_i32_e32 vcc, v202, v198
	v_subrev_u32_e32 v202, 39, v180
	s_nop 0
	v_cndmask_b32_e32 v91, v204, v91, vcc
	v_cmp_le_i32_e32 vcc, v202, v198
	v_add_u32_e32 v202, -7, v180
	s_nop 0
	v_cndmask_b32_e32 v108, v204, v108, vcc
	v_cmp_le_i32_e32 vcc, v202, v198
	v_subrev_u32_e32 v202, 38, v180
	s_nop 0
	v_cndmask_b32_e32 v92, v204, v92, vcc
	v_cmp_le_i32_e32 vcc, v202, v198
	v_add_u32_e32 v202, -6, v180
	s_nop 0
	v_cndmask_b32_e32 v109, v204, v109, vcc
	v_cmp_le_i32_e32 vcc, v202, v198
	v_subrev_u32_e32 v202, 37, v180
	s_nop 0
	v_cndmask_b32_e32 v93, v204, v93, vcc
	v_cmp_le_i32_e32 vcc, v202, v198
	v_add_u32_e32 v202, -5, v180
	s_nop 0
	v_cndmask_b32_e32 v110, v204, v110, vcc
	v_cmp_le_i32_e32 vcc, v202, v198
	v_subrev_u32_e32 v202, 36, v180
	v_add_u32_e32 v180, -4, v180
	v_cndmask_b32_e32 v94, v204, v94, vcc
	v_cmp_le_i32_e32 vcc, v202, v198
	s_nop 1
	v_cndmask_b32_e32 v111, v204, v111, vcc
	v_cmp_le_i32_e32 vcc, v180, v198
	s_nop 1
	v_cndmask_b32_e32 v95, v204, v95, vcc
